# P0 (input conversion + weight transposes): nt streaming hint on the 112 one-pass f32 input loads; rest identical to the dry-queue-skip build
# speedup vs baseline: 1.0091x; 1.0062x over previous
; __device__ __forceinline__ void transpose_item(const float* W, int K, int N, int c0, int ncols, bf16_t* WT, int row_off, float scale, LAS float* scr, int item, int lane) {
;     const int nblk = ncols / 32, kb = item / nblk, nb = item % nblk, k0 = 64 * kb, n0 = 32 * nb;
; #pragma unroll 8
;     for (int i = 0; i < 32; ++i) { const int kk = 2 * i + (lane >> 5); scr[kk * 33 + (lane & 31)] = W[(size_t)(k0 + kk) * N + c0 + n0 + (lane & 31)] * scale; }
;     asm volatile("s_waitcnt lgkmcnt(0)" ::: "memory");
.LBB0_24:
	s_lshl_b32 s38, s31, 1
	s_lshl_b32 s39, s15, 1
	v_or_b32_e32 v29, s38, v3
	s_add_i32 s40, s38, 4
	s_add_i32 s41, s39, 4
	s_add_i32 s42, s38, 8
	s_add_i32 s43, s39, 8
	s_add_i32 s44, s38, 12
	s_add_i32 s45, s39, 12
	v_or_b32_e32 v30, s39, v4
	s_add_i32 s46, s38, 16
	s_add_i32 s47, s39, 16
	s_add_i32 s48, s38, 20
	s_add_i32 s49, s39, 20
	s_add_i32 s50, s38, 24
	s_add_i32 s51, s39, 24
	s_add_i32 s52, s38, 28
	s_add_i32 s53, s39, 28
	v_mad_i64_i32 v[32:33], s[36:37], v29, s34, v[22:23]
	v_or_b32_e32 v29, s40, v3
	v_or_b32_e32 v34, s41, v4
	v_or_b32_e32 v40, s42, v3
	v_or_b32_e32 v38, s43, v4
	v_or_b32_e32 v44, s44, v3
	v_or_b32_e32 v42, s45, v4
	v_mad_i64_i32 v[30:31], s[36:37], v30, s34, v[22:23]
	v_or_b32_e32 v48, s46, v3
	v_or_b32_e32 v46, s47, v4
	v_or_b32_e32 v52, s48, v3
	v_or_b32_e32 v50, s49, v4
	v_or_b32_e32 v56, s50, v3
	v_or_b32_e32 v54, s51, v4
	v_or_b32_e32 v60, s52, v3
	v_or_b32_e32 v58, s53, v4
	v_mad_i64_i32 v[34:35], s[36:37], v34, s34, v[22:23]
	v_mad_i64_i32 v[36:37], s[36:37], v29, s34, v[22:23]
	v_mad_i64_i32 v[38:39], s[36:37], v38, s34, v[22:23]
	v_mad_i64_i32 v[40:41], s[36:37], v40, s34, v[22:23]
	v_mad_i64_i32 v[42:43], s[36:37], v42, s34, v[22:23]
	v_mad_i64_i32 v[44:45], s[36:37], v44, s34, v[22:23]
	v_mad_i64_i32 v[46:47], s[36:37], v46, s34, v[22:23]
	v_mad_i64_i32 v[48:49], s[36:37], v48, s34, v[22:23]
	v_mad_i64_i32 v[50:51], s[36:37], v50, s34, v[22:23]
	v_mad_i64_i32 v[52:53], s[36:37], v52, s34, v[22:23]
	v_mad_i64_i32 v[54:55], s[36:37], v54, s34, v[22:23]
	v_mad_i64_i32 v[56:57], s[36:37], v56, s34, v[22:23]
	v_mad_i64_i32 v[58:59], s[36:37], v58, s34, v[22:23]
	v_mad_i64_i32 v[60:61], s[36:37], v60, s34, v[22:23]
	global_load_dword v30, v[30:31], off nt
	s_nop 0
	global_load_dword v31, v[32:33], off nt
	s_nop 0
	global_load_dword v32, v[34:35], off nt
	global_load_dword v33, v[36:37], off nt
	s_nop 0
	global_load_dword v34, v[38:39], off nt
	global_load_dword v35, v[40:41], off nt
	global_load_dword v36, v[42:43], off nt
	global_load_dword v37, v[44:45], off nt
	s_nop 0
	global_load_dword v38, v[46:47], off nt
	global_load_dword v39, v[48:49], off nt
	global_load_dword v40, v[50:51], off nt
	global_load_dword v41, v[52:53], off nt
	global_load_dword v42, v[54:55], off nt
	global_load_dword v43, v[56:57], off nt
	global_load_dword v44, v[58:59], off nt
	global_load_dword v45, v[60:61], off nt
	v_or_b32_e32 v46, s39, v0
	v_or_b32_e32 v29, s38, v1
	v_mad_u64_u32 v[46:47], s[36:37], v46, s33, v[2:3]
	s_add_i32 s15, s15, 16
	s_add_i32 s31, s31, 16
	s_add_i32 s35, s35, -16
	v_mad_u64_u32 v[48:49], s[36:37], v29, s33, v[2:3]
	v_or_b32_e32 v47, s41, v0
	v_or_b32_e32 v29, s40, v1
	v_or_b32_e32 v49, s42, v1
	v_or_b32_e32 v54, s43, v0
	v_or_b32_e32 v60, s44, v1
	v_or_b32_e32 v58, s45, v0
	v_or_b32_e32 v64, s46, v1
	v_or_b32_e32 v62, s47, v0
	v_or_b32_e32 v68, s48, v1
	v_or_b32_e32 v66, s49, v0
	v_or_b32_e32 v72, s50, v1
	v_or_b32_e32 v70, s51, v0
	v_or_b32_e32 v76, s52, v1
	v_or_b32_e32 v74, s53, v0
	s_cmp_lg_u32 s35, 0
	v_mad_u64_u32 v[50:51], s[36:37], v47, s33, v[2:3]
	v_mad_u64_u32 v[52:53], s[36:37], v29, s33, v[2:3]
	v_mad_u64_u32 v[54:55], s[36:37], v54, s33, v[2:3]
	v_mad_u64_u32 v[56:57], s[36:37], v49, s33, v[2:3]
	v_mad_u64_u32 v[58:59], s[36:37], v58, s33, v[2:3]
	v_mad_u64_u32 v[60:61], s[36:37], v60, s33, v[2:3]
	v_mad_u64_u32 v[62:63], s[36:37], v62, s33, v[2:3]
	v_mad_u64_u32 v[64:65], s[36:37], v64, s33, v[2:3]
	v_mad_u64_u32 v[66:67], s[36:37], v66, s33, v[2:3]
	v_mad_u64_u32 v[68:69], s[36:37], v68, s33, v[2:3]
	v_mad_u64_u32 v[70:71], s[36:37], v70, s33, v[2:3]
	v_mad_u64_u32 v[72:73], s[36:37], v72, s33, v[2:3]
	v_mad_u64_u32 v[74:75], s[36:37], v74, s33, v[2:3]
	v_mad_u64_u32 v[76:77], s[36:37], v76, s33, v[2:3]
	s_waitcnt vmcnt(14)
	v_pk_mul_f32 v[30:31], v[30:31], s[2:3] op_sel_hi:[1,0]
	ds_write_b32 v46, v30
	ds_write_b32 v48, v31
	s_waitcnt vmcnt(12)
	v_pk_mul_f32 v[30:31], v[32:33], s[2:3] op_sel_hi:[1,0]
	s_waitcnt vmcnt(10)
	v_pk_mul_f32 v[32:33], v[34:35], s[2:3] op_sel_hi:[1,0]
	s_waitcnt vmcnt(8)
	v_pk_mul_f32 v[34:35], v[36:37], s[2:3] op_sel_hi:[1,0]
	s_waitcnt vmcnt(6)
	v_pk_mul_f32 v[36:37], v[38:39], s[2:3] op_sel_hi:[1,0]
	s_waitcnt vmcnt(4)
	v_pk_mul_f32 v[38:39], v[40:41], s[2:3] op_sel_hi:[1,0]
	s_waitcnt vmcnt(2)
	v_pk_mul_f32 v[40:41], v[42:43], s[2:3] op_sel_hi:[1,0]
	s_waitcnt vmcnt(0)
	v_pk_mul_f32 v[42:43], v[44:45], s[2:3] op_sel_hi:[1,0]
	ds_write_b32 v50, v30
	ds_write_b32 v52, v31
	ds_write_b32 v54, v32
	ds_write_b32 v56, v33
	ds_write_b32 v58, v34
	ds_write_b32 v60, v35
	ds_write_b32 v62, v36
	ds_write_b32 v64, v37
	ds_write_b32 v66, v38
	ds_write_b32 v68, v39
	ds_write_b32 v70, v40
	ds_write_b32 v72, v41
	ds_write_b32 v74, v42
	ds_write_b32 v76, v43
	s_cbranch_scc1 .LBB0_24
; #define LAS __attribute__((address_space(3)))
; __device__ __forceinline__ unsigned cvtpk(float lo, float hi) { return pg8::cvt_pk_bf16(lo, hi); }
; __device__ __forceinline__ void transpose_item(const float* W, int K, int N, int c0, int ncols, bf16_t* WT, int row_off, float scale, LAS float* scr, int item, int lane) {
;     ...
;     asm volatile("s_waitcnt lgkmcnt(0)" ::: "memory");
;     const int c = lane & 7;
; #pragma unroll
;     for (int j = 0; j < 4; ++j) { const int n = (lane >> 3) + 8 * j; const LAS float* s = scr + (8 * c) * 33 + n;
;         u32x4 o; o.x = cvtpk(s[0 * 33], s[1 * 33]); o.y = cvtpk(s[2 * 33], s[3 * 33]); o.z = cvtpk(s[4 * 33], s[5 * 33]); o.w = cvtpk(s[6 * 33], s[7 * 33]);
;         *(u32x4*)(WT + (size_t)(row_off + n0 + n) * K + k0 + 8 * c) = o; }
;     asm volatile("s_waitcnt lgkmcnt(0)" ::: "memory");
	s_waitcnt lgkmcnt(0)
	ds_read2_b32 v[22:23], v25 offset0:33 offset1:41
	ds_read2_b32 v[34:35], v25 offset1:8
	ds_read2_b32 v[36:37], v25 offset0:66 offset1:74
	ds_read2_b32 v[38:39], v25 offset0:99 offset1:107
	ds_read2_b32 v[40:41], v25 offset0:132 offset1:140
	ds_read2_b32 v[42:43], v25 offset0:165 offset1:173
	ds_read2_b32 v[44:45], v25 offset0:198 offset1:206
	ds_read2_b32 v[46:47], v25 offset0:231 offset1:239
	v_or_b32_e32 v50, s14, v24
	s_ashr_i32 s31, s30, 31
	v_ashrrev_i32_e32 v51, 31, v50
	v_lshl_add_u64 v[48:49], s[30:31], 1, v[6:7]
	v_lshlrev_b64 v[50:51], 11, v[50:51]
	s_waitcnt lgkmcnt(6)
	v_cvt_pk_bf16_f32 v30, v34, v22
	s_waitcnt lgkmcnt(4)
	v_cvt_pk_bf16_f32 v31, v36, v38
	s_waitcnt lgkmcnt(2)
	v_cvt_pk_bf16_f32 v32, v40, v42
	s_waitcnt lgkmcnt(0)
	v_cvt_pk_bf16_f32 v33, v44, v46
	v_lshl_add_u64 v[50:51], v[48:49], 0, v[50:51]
	v_or_b32_e32 v22, s14, v26
	global_store_dwordx4 v[50:51], v[30:33], off
	s_nop 1
	v_cvt_pk_bf16_f32 v30, v35, v23
	v_ashrrev_i32_e32 v23, 31, v22
	v_cvt_pk_bf16_f32 v31, v37, v39
	v_cvt_pk_bf16_f32 v32, v41, v43
	v_cvt_pk_bf16_f32 v33, v45, v47
	v_lshlrev_b64 v[22:23], 11, v[22:23]
	ds_read2_b32 v[34:35], v25 offset0:49 offset1:57
	ds_read2_b32 v[36:37], v25 offset0:16 offset1:24
	ds_read2_b32 v[38:39], v25 offset0:82 offset1:90
	ds_read2_b32 v[40:41], v25 offset0:115 offset1:123
	ds_read2_b32 v[42:43], v25 offset0:148 offset1:156
	ds_read2_b32 v[44:45], v25 offset0:181 offset1:189
	ds_read2_b32 v[46:47], v25 offset0:214 offset1:222
	ds_read2_b32 v[50:51], v25 offset0:247 offset1:255
	v_lshl_add_u64 v[22:23], v[48:49], 0, v[22:23]
	global_store_dwordx4 v[22:23], v[30:33], off
	v_or_b32_e32 v22, s14, v27
	v_ashrrev_i32_e32 v23, 31, v22
	v_lshlrev_b64 v[22:23], 11, v[22:23]
	s_waitcnt lgkmcnt(6)
	v_cvt_pk_bf16_f32 v30, v36, v34
	s_waitcnt lgkmcnt(4)
	v_cvt_pk_bf16_f32 v31, v38, v40
	s_waitcnt lgkmcnt(2)
	v_cvt_pk_bf16_f32 v32, v42, v44
	s_waitcnt lgkmcnt(0)
	v_cvt_pk_bf16_f32 v33, v46, v50
	v_lshl_add_u64 v[22:23], v[48:49], 0, v[22:23]
	global_store_dwordx4 v[22:23], v[30:33], off
	v_or_b32_e32 v22, s14, v28
	v_ashrrev_i32_e32 v23, 31, v22
	v_lshlrev_b64 v[22:23], 11, v[22:23]
	v_cvt_pk_bf16_f32 v30, v37, v35
	v_cvt_pk_bf16_f32 v31, v39, v41
	v_cvt_pk_bf16_f32 v32, v43, v45
	v_cvt_pk_bf16_f32 v33, v47, v51
	v_lshl_add_u64 v[22:23], v[48:49], 0, v[22:23]
	global_store_dwordx4 v[22:23], v[30:33], off
	s_waitcnt lgkmcnt(0)
	s_mov_b32 s35, s3

; #define LAS __attribute__((address_space(3)))
; __device__ __forceinline__ unsigned cvtpk(float lo, float hi) { return pg8::cvt_pk_bf16(lo, hi); }
; __device__ __forceinline__ void transpose_item(const float* W, int K, int N, int c0, int ncols, bf16_t* WT, int row_off, float scale, LAS float* scr, int item, int lane) {
;     const int nblk = ncols / 32, kb = item / nblk, nb = item % nblk, k0 = 64 * kb, n0 = 32 * nb;
; #pragma unroll 8
;     for (int i = 0; i < 32; ++i) { const int kk = 2 * i + (lane >> 5); scr[kk * 33 + (lane & 31)] = W[(size_t)(k0 + kk) * N + c0 + n0 + (lane & 31)] * scale; }
;     asm volatile("s_waitcnt lgkmcnt(0)" ::: "memory");
;     const int c = lane & 7;
; #pragma unroll
;     for (int j = 0; j < 4; ++j) { const int n = (lane >> 3) + 8 * j; const LAS float* s = scr + (8 * c) * 33 + n;
;         u32x4 o; o.x = cvtpk(s[0 * 33], s[1 * 33]); o.y = cvtpk(s[2 * 33], s[3 * 33]); o.z = cvtpk(s[4 * 33], s[5 * 33]); o.w = cvtpk(s[6 * 33], s[7 * 33]);
;         *(u32x4*)(WT + (size_t)(row_off + n0 + n) * K + k0 + 8 * c) = o; }
;     asm volatile("s_waitcnt lgkmcnt(0)" ::: "memory");
.LBB0_31:
	s_lshl_b32 s37, s15, 1
	s_lshl_b32 s40, s31, 1
	v_or_b32_e32 v29, s37, v3
	v_or_b32_e32 v30, s40, v4
	s_add_i32 s41, s37, 4
	s_add_i32 s42, s40, 4
	s_add_i32 s43, s37, 8
	s_add_i32 s44, s40, 8
	s_add_i32 s45, s37, 12
	s_add_i32 s46, s40, 12
	s_add_i32 s47, s37, 16
	s_add_i32 s48, s40, 16
	s_add_i32 s49, s37, 20
	s_add_i32 s50, s40, 20
	s_add_i32 s51, s37, 24
	s_add_i32 s52, s40, 24
	s_add_i32 s53, s37, 28
	s_add_i32 s54, s40, 28
	v_mad_i64_i32 v[30:31], s[38:39], v30, s34, v[22:23]
	v_mad_i64_i32 v[32:33], s[38:39], v29, s34, v[22:23]
	v_or_b32_e32 v29, s41, v3
	v_or_b32_e32 v34, s42, v4
	v_or_b32_e32 v40, s43, v3
	v_or_b32_e32 v38, s44, v4
	v_or_b32_e32 v44, s45, v3
	v_or_b32_e32 v42, s46, v4
	v_or_b32_e32 v48, s47, v3
	v_or_b32_e32 v46, s48, v4
	v_or_b32_e32 v52, s49, v3
	v_or_b32_e32 v50, s50, v4
	v_or_b32_e32 v56, s51, v3
	v_or_b32_e32 v54, s52, v4
	v_or_b32_e32 v60, s53, v3
	v_or_b32_e32 v58, s54, v4
	v_mad_i64_i32 v[34:35], s[38:39], v34, s34, v[22:23]
	v_mad_i64_i32 v[36:37], s[38:39], v29, s34, v[22:23]
	v_mad_i64_i32 v[38:39], s[38:39], v38, s34, v[22:23]
	v_mad_i64_i32 v[40:41], s[38:39], v40, s34, v[22:23]
	v_mad_i64_i32 v[42:43], s[38:39], v42, s34, v[22:23]
	v_mad_i64_i32 v[44:45], s[38:39], v44, s34, v[22:23]
	v_mad_i64_i32 v[46:47], s[38:39], v46, s34, v[22:23]
	v_mad_i64_i32 v[48:49], s[38:39], v48, s34, v[22:23]
	v_mad_i64_i32 v[50:51], s[38:39], v50, s34, v[22:23]
	v_mad_i64_i32 v[52:53], s[38:39], v52, s34, v[22:23]
	v_mad_i64_i32 v[54:55], s[38:39], v54, s34, v[22:23]
	v_mad_i64_i32 v[56:57], s[38:39], v56, s34, v[22:23]
	v_mad_i64_i32 v[58:59], s[38:39], v58, s34, v[22:23]
	v_mad_i64_i32 v[60:61], s[38:39], v60, s34, v[22:23]
	global_load_dword v29, v[30:31], off nt
	global_load_dword v62, v[32:33], off nt
	global_load_dword v63, v[34:35], off nt
	global_load_dword v64, v[36:37], off nt
	global_load_dword v65, v[38:39], off nt
	global_load_dword v66, v[40:41], off nt
	global_load_dword v67, v[42:43], off nt
	global_load_dword v68, v[44:45], off nt
	global_load_dword v69, v[46:47], off nt
	global_load_dword v70, v[48:49], off nt
	global_load_dword v71, v[50:51], off nt
	global_load_dword v72, v[52:53], off nt
	global_load_dword v73, v[54:55], off nt
	global_load_dword v74, v[56:57], off nt
	global_load_dword v75, v[58:59], off nt
	global_load_dword v76, v[60:61], off nt
	v_or_b32_e32 v32, s37, v1
	v_or_b32_e32 v30, s40, v0
	s_add_i32 s31, s31, 16
	s_add_i32 s15, s15, 16
	s_add_i32 s36, s36, -16
	v_mad_u64_u32 v[30:31], s[38:39], v30, s33, v[2:3]
	v_mad_u64_u32 v[32:33], s[38:39], v32, s33, v[2:3]
	v_or_b32_e32 v31, s41, v1
	v_or_b32_e32 v33, s42, v0
	v_or_b32_e32 v40, s43, v1
	v_or_b32_e32 v38, s44, v0
	v_or_b32_e32 v44, s45, v1
	v_or_b32_e32 v42, s46, v0
	v_or_b32_e32 v48, s47, v1
	v_or_b32_e32 v46, s48, v0
	v_or_b32_e32 v52, s49, v1
	v_or_b32_e32 v50, s50, v0
	v_or_b32_e32 v56, s51, v1
	v_or_b32_e32 v54, s52, v0
	v_or_b32_e32 v60, s53, v1
	v_or_b32_e32 v58, s54, v0
	s_cmp_lg_u32 s36, 0
	v_mad_u64_u32 v[34:35], s[38:39], v33, s33, v[2:3]
	v_mad_u64_u32 v[36:37], s[38:39], v31, s33, v[2:3]
	v_mad_u64_u32 v[38:39], s[38:39], v38, s33, v[2:3]
	v_mad_u64_u32 v[40:41], s[38:39], v40, s33, v[2:3]
	v_mad_u64_u32 v[42:43], s[38:39], v42, s33, v[2:3]
	v_mad_u64_u32 v[44:45], s[38:39], v44, s33, v[2:3]
	v_mad_u64_u32 v[46:47], s[38:39], v46, s33, v[2:3]
	v_mad_u64_u32 v[48:49], s[38:39], v48, s33, v[2:3]
	v_mad_u64_u32 v[50:51], s[38:39], v50, s33, v[2:3]
	v_mad_u64_u32 v[52:53], s[38:39], v52, s33, v[2:3]
	v_mad_u64_u32 v[54:55], s[38:39], v54, s33, v[2:3]
	v_mad_u64_u32 v[56:57], s[38:39], v56, s33, v[2:3]
	v_mad_u64_u32 v[58:59], s[38:39], v58, s33, v[2:3]
	v_mad_u64_u32 v[60:61], s[38:39], v60, s33, v[2:3]
	s_waitcnt vmcnt(15)
	ds_write_b32 v30, v29
	s_waitcnt vmcnt(14)
	ds_write_b32 v32, v62
	s_waitcnt vmcnt(13)
	ds_write_b32 v34, v63
	s_waitcnt vmcnt(12)
	ds_write_b32 v36, v64
	s_waitcnt vmcnt(11)
	ds_write_b32 v38, v65
	s_waitcnt vmcnt(10)
	ds_write_b32 v40, v66
	s_waitcnt vmcnt(9)
	ds_write_b32 v42, v67
	s_waitcnt vmcnt(8)
	ds_write_b32 v44, v68
	s_waitcnt vmcnt(7)
	ds_write_b32 v46, v69
	s_waitcnt vmcnt(6)
	ds_write_b32 v48, v70
	s_waitcnt vmcnt(5)
	ds_write_b32 v50, v71
	s_waitcnt vmcnt(4)
	ds_write_b32 v52, v72
	s_waitcnt vmcnt(3)
	ds_write_b32 v54, v73
	s_waitcnt vmcnt(2)
	ds_write_b32 v56, v74
	s_waitcnt vmcnt(1)
	ds_write_b32 v58, v75
	s_waitcnt vmcnt(0)
	ds_write_b32 v60, v76
	s_cbranch_scc1 .LBB0_31
	s_waitcnt lgkmcnt(0)
	ds_read2_b32 v[22:23], v25 offset0:33 offset1:41
	ds_read2_b32 v[34:35], v25 offset1:8
	ds_read2_b32 v[36:37], v25 offset0:66 offset1:74
	ds_read2_b32 v[38:39], v25 offset0:99 offset1:107
	ds_read2_b32 v[40:41], v25 offset0:132 offset1:140
	ds_read2_b32 v[42:43], v25 offset0:165 offset1:173
	ds_read2_b32 v[44:45], v25 offset0:198 offset1:206
	ds_read2_b32 v[46:47], v25 offset0:231 offset1:239
	s_addk_i32 s30, 0x400
	s_ashr_i32 s15, s14, 31
	v_or_b32_e32 v4, s30, v24
	v_lshl_add_u64 v[48:49], s[14:15], 1, v[6:7]
	v_lshlrev_b64 v[50:51], 11, v[4:5]
	s_waitcnt lgkmcnt(6)
	v_cvt_pk_bf16_f32 v30, v34, v22
	s_waitcnt lgkmcnt(4)
	v_cvt_pk_bf16_f32 v31, v36, v38
	s_waitcnt lgkmcnt(2)
	v_cvt_pk_bf16_f32 v32, v40, v42
	s_waitcnt lgkmcnt(0)
	v_cvt_pk_bf16_f32 v33, v44, v46
	v_lshl_add_u64 v[50:51], v[48:49], 0, v[50:51]
	global_store_dwordx4 v[50:51], v[30:33], off
	v_or_b32_e32 v4, s30, v26
	s_nop 0
	v_cvt_pk_bf16_f32 v30, v35, v23
	v_cvt_pk_bf16_f32 v31, v37, v39
	v_cvt_pk_bf16_f32 v32, v41, v43
	v_cvt_pk_bf16_f32 v33, v45, v47
	ds_read2_b32 v[34:35], v25 offset0:49 offset1:57
	ds_read2_b32 v[36:37], v25 offset0:16 offset1:24
	ds_read2_b32 v[38:39], v25 offset0:82 offset1:90
	ds_read2_b32 v[40:41], v25 offset0:115 offset1:123
	ds_read2_b32 v[42:43], v25 offset0:148 offset1:156
	ds_read2_b32 v[44:45], v25 offset0:181 offset1:189
	ds_read2_b32 v[46:47], v25 offset0:214 offset1:222
	ds_read2_b32 v[50:51], v25 offset0:247 offset1:255
	v_lshlrev_b64 v[22:23], 11, v[4:5]
	v_lshl_add_u64 v[22:23], v[48:49], 0, v[22:23]
	v_or_b32_e32 v4, s30, v27
	global_store_dwordx4 v[22:23], v[30:33], off
	v_lshlrev_b64 v[22:23], 11, v[4:5]
	v_lshl_add_u64 v[22:23], v[48:49], 0, v[22:23]
	s_waitcnt lgkmcnt(6)
	v_cvt_pk_bf16_f32 v30, v36, v34
	s_waitcnt lgkmcnt(4)
	v_cvt_pk_bf16_f32 v31, v38, v40
	s_waitcnt lgkmcnt(2)
	v_cvt_pk_bf16_f32 v32, v42, v44
	s_waitcnt lgkmcnt(0)
	v_cvt_pk_bf16_f32 v33, v46, v50
	v_or_b32_e32 v4, s30, v28
	global_store_dwordx4 v[22:23], v[30:33], off
	v_lshlrev_b64 v[22:23], 11, v[4:5]
	v_lshl_add_u64 v[22:23], v[48:49], 0, v[22:23]
	v_cvt_pk_bf16_f32 v30, v37, v35
	v_cvt_pk_bf16_f32 v31, v39, v41
	v_cvt_pk_bf16_f32 v32, v43, v45
	v_cvt_pk_bf16_f32 v33, v47, v51
	global_store_dwordx4 v[22:23], v[30:33], off
	s_waitcnt lgkmcnt(0)

; #define LAS __attribute__((address_space(3)))
; __device__ __forceinline__ unsigned cvtpk(float lo, float hi) { return pg8::cvt_pk_bf16(lo, hi); }
; __device__ __forceinline__ void transpose_item(const float* W, int K, int N, int c0, int ncols, bf16_t* WT, int row_off, float scale, LAS float* scr, int item, int lane) {
;     const int nblk = ncols / 32, kb = item / nblk, nb = item % nblk, k0 = 64 * kb, n0 = 32 * nb;
; #pragma unroll 8
;     for (int i = 0; i < 32; ++i) { const int kk = 2 * i + (lane >> 5); scr[kk * 33 + (lane & 31)] = W[(size_t)(k0 + kk) * N + c0 + n0 + (lane & 31)] * scale; }
;     asm volatile("s_waitcnt lgkmcnt(0)" ::: "memory");
;     const int c = lane & 7;
; #pragma unroll
;     for (int j = 0; j < 4; ++j) { const int n = (lane >> 3) + 8 * j; const LAS float* s = scr + (8 * c) * 33 + n;
;         u32x4 o; o.x = cvtpk(s[0 * 33], s[1 * 33]); o.y = cvtpk(s[2 * 33], s[3 * 33]); o.z = cvtpk(s[4 * 33], s[5 * 33]); o.w = cvtpk(s[6 * 33], s[7 * 33]);
;         *(u32x4*)(WT + (size_t)(row_off + n0 + n) * K + k0 + 8 * c) = o; }
;     asm volatile("s_waitcnt lgkmcnt(0)" ::: "memory");
.LBB0_38:
	s_lshl_b32 s37, s15, 1
	s_lshl_b32 s40, s31, 1
	v_or_b32_e32 v29, s37, v3
	v_or_b32_e32 v30, s40, v4
	s_add_i32 s41, s37, 4
	s_add_i32 s42, s40, 4
	s_add_i32 s43, s37, 8
	s_add_i32 s44, s40, 8
	s_add_i32 s45, s37, 12
	s_add_i32 s46, s40, 12
	s_add_i32 s47, s37, 16
	s_add_i32 s48, s40, 16
	s_add_i32 s49, s37, 20
	s_add_i32 s50, s40, 20
	s_add_i32 s51, s37, 24
	s_add_i32 s52, s40, 24
	s_add_i32 s53, s37, 28
	s_add_i32 s54, s40, 28
	v_mad_i64_i32 v[30:31], s[38:39], v30, s34, v[22:23]
	v_mad_i64_i32 v[32:33], s[38:39], v29, s34, v[22:23]
	v_or_b32_e32 v29, s41, v3
	v_or_b32_e32 v34, s42, v4
	v_or_b32_e32 v40, s43, v3
	v_or_b32_e32 v38, s44, v4
	v_or_b32_e32 v44, s45, v3
	v_or_b32_e32 v42, s46, v4
	v_or_b32_e32 v48, s47, v3
	v_or_b32_e32 v46, s48, v4
	v_or_b32_e32 v52, s49, v3
	v_or_b32_e32 v50, s50, v4
	v_or_b32_e32 v56, s51, v3
	v_or_b32_e32 v54, s52, v4
	v_or_b32_e32 v60, s53, v3
	v_or_b32_e32 v58, s54, v4
	v_mad_i64_i32 v[34:35], s[38:39], v34, s34, v[22:23]
	v_mad_i64_i32 v[36:37], s[38:39], v29, s34, v[22:23]
	v_mad_i64_i32 v[38:39], s[38:39], v38, s34, v[22:23]
	v_mad_i64_i32 v[40:41], s[38:39], v40, s34, v[22:23]
	v_mad_i64_i32 v[42:43], s[38:39], v42, s34, v[22:23]
	v_mad_i64_i32 v[44:45], s[38:39], v44, s34, v[22:23]
	v_mad_i64_i32 v[46:47], s[38:39], v46, s34, v[22:23]
	v_mad_i64_i32 v[48:49], s[38:39], v48, s34, v[22:23]
	v_mad_i64_i32 v[50:51], s[38:39], v50, s34, v[22:23]
	v_mad_i64_i32 v[52:53], s[38:39], v52, s34, v[22:23]
	v_mad_i64_i32 v[54:55], s[38:39], v54, s34, v[22:23]
	v_mad_i64_i32 v[56:57], s[38:39], v56, s34, v[22:23]
	v_mad_i64_i32 v[58:59], s[38:39], v58, s34, v[22:23]
	v_mad_i64_i32 v[60:61], s[38:39], v60, s34, v[22:23]
	global_load_dword v29, v[30:31], off nt
	global_load_dword v62, v[32:33], off nt
	global_load_dword v63, v[34:35], off nt
	global_load_dword v64, v[36:37], off nt
	global_load_dword v65, v[38:39], off nt
	global_load_dword v66, v[40:41], off nt
	global_load_dword v67, v[42:43], off nt
	global_load_dword v68, v[44:45], off nt
	global_load_dword v69, v[46:47], off nt
	global_load_dword v70, v[48:49], off nt
	global_load_dword v71, v[50:51], off nt
	global_load_dword v72, v[52:53], off nt
	global_load_dword v73, v[54:55], off nt
	global_load_dword v74, v[56:57], off nt
	global_load_dword v75, v[58:59], off nt
	global_load_dword v76, v[60:61], off nt
	v_or_b32_e32 v32, s37, v1
	v_or_b32_e32 v30, s40, v0
	s_add_i32 s31, s31, 16
	s_add_i32 s15, s15, 16
	s_add_i32 s36, s36, -16
	v_mad_u64_u32 v[30:31], s[38:39], v30, s33, v[2:3]
	v_mad_u64_u32 v[32:33], s[38:39], v32, s33, v[2:3]
	v_or_b32_e32 v31, s41, v1
	v_or_b32_e32 v33, s42, v0
	v_or_b32_e32 v40, s43, v1
	v_or_b32_e32 v38, s44, v0
	v_or_b32_e32 v44, s45, v1
	v_or_b32_e32 v42, s46, v0
	v_or_b32_e32 v48, s47, v1
	v_or_b32_e32 v46, s48, v0
	v_or_b32_e32 v52, s49, v1
	v_or_b32_e32 v50, s50, v0
	v_or_b32_e32 v56, s51, v1
	v_or_b32_e32 v54, s52, v0
	v_or_b32_e32 v60, s53, v1
	v_or_b32_e32 v58, s54, v0
	s_cmp_lg_u32 s36, 0
	v_mad_u64_u32 v[34:35], s[38:39], v33, s33, v[2:3]
	v_mad_u64_u32 v[36:37], s[38:39], v31, s33, v[2:3]
	v_mad_u64_u32 v[38:39], s[38:39], v38, s33, v[2:3]
	v_mad_u64_u32 v[40:41], s[38:39], v40, s33, v[2:3]
	v_mad_u64_u32 v[42:43], s[38:39], v42, s33, v[2:3]
	v_mad_u64_u32 v[44:45], s[38:39], v44, s33, v[2:3]
	v_mad_u64_u32 v[46:47], s[38:39], v46, s33, v[2:3]
	v_mad_u64_u32 v[48:49], s[38:39], v48, s33, v[2:3]
	v_mad_u64_u32 v[50:51], s[38:39], v50, s33, v[2:3]
	v_mad_u64_u32 v[52:53], s[38:39], v52, s33, v[2:3]
	v_mad_u64_u32 v[54:55], s[38:39], v54, s33, v[2:3]
	v_mad_u64_u32 v[56:57], s[38:39], v56, s33, v[2:3]
	v_mad_u64_u32 v[58:59], s[38:39], v58, s33, v[2:3]
	v_mad_u64_u32 v[60:61], s[38:39], v60, s33, v[2:3]
	s_waitcnt vmcnt(15)
	ds_write_b32 v30, v29
	s_waitcnt vmcnt(14)
	ds_write_b32 v32, v62
	s_waitcnt vmcnt(13)
	ds_write_b32 v34, v63
	s_waitcnt vmcnt(12)
	ds_write_b32 v36, v64
	s_waitcnt vmcnt(11)
	ds_write_b32 v38, v65
	s_waitcnt vmcnt(10)
	ds_write_b32 v40, v66
	s_waitcnt vmcnt(9)
	ds_write_b32 v42, v67
	s_waitcnt vmcnt(8)
	ds_write_b32 v44, v68
	s_waitcnt vmcnt(7)
	ds_write_b32 v46, v69
	s_waitcnt vmcnt(6)
	ds_write_b32 v48, v70
	s_waitcnt vmcnt(5)
	ds_write_b32 v50, v71
	s_waitcnt vmcnt(4)
	ds_write_b32 v52, v72
	s_waitcnt vmcnt(3)
	ds_write_b32 v54, v73
	s_waitcnt vmcnt(2)
	ds_write_b32 v56, v74
	s_waitcnt vmcnt(1)
	ds_write_b32 v58, v75
	s_waitcnt vmcnt(0)
	ds_write_b32 v60, v76
	s_cbranch_scc1 .LBB0_38
	s_waitcnt lgkmcnt(0)
	ds_read2_b32 v[22:23], v25 offset0:33 offset1:41
	ds_read2_b32 v[34:35], v25 offset1:8
	ds_read2_b32 v[36:37], v25 offset0:66 offset1:74
	ds_read2_b32 v[38:39], v25 offset0:99 offset1:107
	ds_read2_b32 v[40:41], v25 offset0:132 offset1:140
	ds_read2_b32 v[42:43], v25 offset0:165 offset1:173
	ds_read2_b32 v[44:45], v25 offset0:198 offset1:206
	ds_read2_b32 v[46:47], v25 offset0:231 offset1:239
	s_addk_i32 s30, 0x1a00
	s_ashr_i32 s15, s14, 31
	v_or_b32_e32 v4, s30, v24
	v_lshl_add_u64 v[48:49], s[14:15], 1, v[6:7]
	v_lshlrev_b64 v[50:51], 11, v[4:5]
	s_waitcnt lgkmcnt(6)
	v_cvt_pk_bf16_f32 v30, v34, v22
	s_waitcnt lgkmcnt(4)
	v_cvt_pk_bf16_f32 v31, v36, v38
	s_waitcnt lgkmcnt(2)
	v_cvt_pk_bf16_f32 v32, v40, v42
	s_waitcnt lgkmcnt(0)
	v_cvt_pk_bf16_f32 v33, v44, v46
	v_lshl_add_u64 v[50:51], v[48:49], 0, v[50:51]
	global_store_dwordx4 v[50:51], v[30:33], off
	v_or_b32_e32 v4, s30, v26
	s_nop 0
	v_cvt_pk_bf16_f32 v30, v35, v23
	v_cvt_pk_bf16_f32 v31, v37, v39
	v_cvt_pk_bf16_f32 v32, v41, v43
	v_cvt_pk_bf16_f32 v33, v45, v47
	ds_read2_b32 v[34:35], v25 offset0:49 offset1:57
	ds_read2_b32 v[36:37], v25 offset0:16 offset1:24
	ds_read2_b32 v[38:39], v25 offset0:82 offset1:90
	ds_read2_b32 v[40:41], v25 offset0:115 offset1:123
	ds_read2_b32 v[42:43], v25 offset0:148 offset1:156
	ds_read2_b32 v[44:45], v25 offset0:181 offset1:189
	ds_read2_b32 v[46:47], v25 offset0:214 offset1:222
	ds_read2_b32 v[50:51], v25 offset0:247 offset1:255
	v_lshlrev_b64 v[22:23], 11, v[4:5]
	v_lshl_add_u64 v[22:23], v[48:49], 0, v[22:23]
	v_or_b32_e32 v4, s30, v27
	global_store_dwordx4 v[22:23], v[30:33], off
	v_lshlrev_b64 v[22:23], 11, v[4:5]
	v_lshl_add_u64 v[22:23], v[48:49], 0, v[22:23]
	s_waitcnt lgkmcnt(6)
	v_cvt_pk_bf16_f32 v30, v36, v34
	s_waitcnt lgkmcnt(4)
	v_cvt_pk_bf16_f32 v31, v38, v40
	s_waitcnt lgkmcnt(2)
	v_cvt_pk_bf16_f32 v32, v42, v44
	s_waitcnt lgkmcnt(0)
	v_cvt_pk_bf16_f32 v33, v46, v50
	v_or_b32_e32 v4, s30, v28
	global_store_dwordx4 v[22:23], v[30:33], off
	v_lshlrev_b64 v[22:23], 11, v[4:5]
	v_lshl_add_u64 v[22:23], v[48:49], 0, v[22:23]
	v_cvt_pk_bf16_f32 v30, v37, v35
	v_cvt_pk_bf16_f32 v31, v39, v41
	v_cvt_pk_bf16_f32 v32, v43, v45
	v_cvt_pk_bf16_f32 v33, v47, v51
	global_store_dwordx4 v[22:23], v[30:33], off
	s_waitcnt lgkmcnt(0)

; #define LAS __attribute__((address_space(3)))
; __device__ __forceinline__ unsigned cvtpk(float lo, float hi) { return pg8::cvt_pk_bf16(lo, hi); }
; __device__ __forceinline__ void transpose_item(const float* W, int K, int N, int c0, int ncols, bf16_t* WT, int row_off, float scale, LAS float* scr, int item, int lane) {
;     const int nblk = ncols / 32, kb = item / nblk, nb = item % nblk, k0 = 64 * kb, n0 = 32 * nb;
; #pragma unroll 8
;     for (int i = 0; i < 32; ++i) { const int kk = 2 * i + (lane >> 5); scr[kk * 33 + (lane & 31)] = W[(size_t)(k0 + kk) * N + c0 + n0 + (lane & 31)] * scale; }
;     asm volatile("s_waitcnt lgkmcnt(0)" ::: "memory");
;     const int c = lane & 7;
; #pragma unroll
;     for (int j = 0; j < 4; ++j) { const int n = (lane >> 3) + 8 * j; const LAS float* s = scr + (8 * c) * 33 + n;
;         u32x4 o; o.x = cvtpk(s[0 * 33], s[1 * 33]); o.y = cvtpk(s[2 * 33], s[3 * 33]); o.z = cvtpk(s[4 * 33], s[5 * 33]); o.w = cvtpk(s[6 * 33], s[7 * 33]);
;         *(u32x4*)(WT + (size_t)(row_off + n0 + n) * K + k0 + 8 * c) = o; }
;     asm volatile("s_waitcnt lgkmcnt(0)" ::: "memory");
.LBB0_45:
	s_lshl_b32 s37, s15, 1
	s_lshl_b32 s40, s31, 1
	v_or_b32_e32 v29, s37, v3
	s_add_i32 s41, s37, 4
	s_add_i32 s42, s40, 4
	s_add_i32 s43, s37, 8
	s_add_i32 s44, s40, 8
	s_add_i32 s45, s37, 12
	s_add_i32 s46, s40, 12
	v_or_b32_e32 v30, s40, v4
	s_add_i32 s47, s37, 16
	s_add_i32 s48, s40, 16
	s_add_i32 s49, s37, 20
	s_add_i32 s50, s40, 20
	s_add_i32 s51, s37, 24
	s_add_i32 s52, s40, 24
	s_add_i32 s53, s37, 28
	s_add_i32 s54, s40, 28
	v_mad_i64_i32 v[32:33], s[38:39], v29, s34, v[22:23]
	v_or_b32_e32 v29, s41, v3
	v_or_b32_e32 v34, s42, v4
	v_or_b32_e32 v40, s43, v3
	v_or_b32_e32 v38, s44, v4
	v_or_b32_e32 v44, s45, v3
	v_or_b32_e32 v42, s46, v4
	v_mad_i64_i32 v[30:31], s[38:39], v30, s34, v[22:23]
	v_or_b32_e32 v48, s47, v3
	v_or_b32_e32 v46, s48, v4
	v_or_b32_e32 v52, s49, v3
	v_or_b32_e32 v50, s50, v4
	v_or_b32_e32 v56, s51, v3
	v_or_b32_e32 v54, s52, v4
	v_or_b32_e32 v60, s53, v3
	v_or_b32_e32 v58, s54, v4
	v_mad_i64_i32 v[34:35], s[38:39], v34, s34, v[22:23]
	v_mad_i64_i32 v[36:37], s[38:39], v29, s34, v[22:23]
	v_mad_i64_i32 v[38:39], s[38:39], v38, s34, v[22:23]
	v_mad_i64_i32 v[40:41], s[38:39], v40, s34, v[22:23]
	v_mad_i64_i32 v[42:43], s[38:39], v42, s34, v[22:23]
	v_mad_i64_i32 v[44:45], s[38:39], v44, s34, v[22:23]
	v_mad_i64_i32 v[46:47], s[38:39], v46, s34, v[22:23]
	v_mad_i64_i32 v[48:49], s[38:39], v48, s34, v[22:23]
	v_mad_i64_i32 v[50:51], s[38:39], v50, s34, v[22:23]
	v_mad_i64_i32 v[52:53], s[38:39], v52, s34, v[22:23]
	v_mad_i64_i32 v[54:55], s[38:39], v54, s34, v[22:23]
	v_mad_i64_i32 v[56:57], s[38:39], v56, s34, v[22:23]
	v_mad_i64_i32 v[58:59], s[38:39], v58, s34, v[22:23]
	v_mad_i64_i32 v[60:61], s[38:39], v60, s34, v[22:23]
	global_load_dword v30, v[30:31], off nt
	s_nop 0
	global_load_dword v31, v[32:33], off nt
	s_nop 0
	global_load_dword v32, v[34:35], off nt
	global_load_dword v33, v[36:37], off nt
	s_nop 0
	global_load_dword v34, v[38:39], off nt
	global_load_dword v35, v[40:41], off nt
	global_load_dword v36, v[42:43], off nt
	global_load_dword v37, v[44:45], off nt
	s_nop 0
	global_load_dword v38, v[46:47], off nt
	global_load_dword v39, v[48:49], off nt
	global_load_dword v40, v[50:51], off nt
	global_load_dword v41, v[52:53], off nt
	global_load_dword v42, v[54:55], off nt
	global_load_dword v43, v[56:57], off nt
	global_load_dword v44, v[58:59], off nt
	global_load_dword v45, v[60:61], off nt
	v_or_b32_e32 v46, s40, v0
	v_or_b32_e32 v29, s37, v1
	v_mad_u64_u32 v[46:47], s[38:39], v46, s33, v[2:3]
	s_add_i32 s31, s31, 16
	s_add_i32 s15, s15, 16
	s_add_i32 s36, s36, -16
	v_mad_u64_u32 v[48:49], s[38:39], v29, s33, v[2:3]
	v_or_b32_e32 v47, s42, v0
	v_or_b32_e32 v29, s41, v1
	v_or_b32_e32 v49, s43, v1
	v_or_b32_e32 v54, s44, v0
	v_or_b32_e32 v60, s45, v1
	v_or_b32_e32 v58, s46, v0
	v_or_b32_e32 v64, s47, v1
	v_or_b32_e32 v62, s48, v0
	v_or_b32_e32 v68, s49, v1
	v_or_b32_e32 v66, s50, v0
	v_or_b32_e32 v72, s51, v1
	v_or_b32_e32 v70, s52, v0
	v_or_b32_e32 v76, s53, v1
	v_or_b32_e32 v74, s54, v0
	s_cmp_lg_u32 s36, 0
	v_mad_u64_u32 v[50:51], s[38:39], v47, s33, v[2:3]
	v_mad_u64_u32 v[52:53], s[38:39], v29, s33, v[2:3]
	v_mad_u64_u32 v[54:55], s[38:39], v54, s33, v[2:3]
	v_mad_u64_u32 v[56:57], s[38:39], v49, s33, v[2:3]
	v_mad_u64_u32 v[58:59], s[38:39], v58, s33, v[2:3]
	v_mad_u64_u32 v[60:61], s[38:39], v60, s33, v[2:3]
	v_mad_u64_u32 v[62:63], s[38:39], v62, s33, v[2:3]
	v_mad_u64_u32 v[64:65], s[38:39], v64, s33, v[2:3]
	v_mad_u64_u32 v[66:67], s[38:39], v66, s33, v[2:3]
	v_mad_u64_u32 v[68:69], s[38:39], v68, s33, v[2:3]
	v_mad_u64_u32 v[70:71], s[38:39], v70, s33, v[2:3]
	v_mad_u64_u32 v[72:73], s[38:39], v72, s33, v[2:3]
	v_mad_u64_u32 v[74:75], s[38:39], v74, s33, v[2:3]
	v_mad_u64_u32 v[76:77], s[38:39], v76, s33, v[2:3]
	s_waitcnt vmcnt(14)
	v_pk_mul_f32 v[30:31], v[30:31], s[2:3] op_sel_hi:[1,0]
	ds_write_b32 v46, v30
	ds_write_b32 v48, v31
	s_waitcnt vmcnt(12)
	v_pk_mul_f32 v[30:31], v[32:33], s[2:3] op_sel_hi:[1,0]
	s_waitcnt vmcnt(10)
	v_pk_mul_f32 v[32:33], v[34:35], s[2:3] op_sel_hi:[1,0]
	s_waitcnt vmcnt(8)
	v_pk_mul_f32 v[34:35], v[36:37], s[2:3] op_sel_hi:[1,0]
	s_waitcnt vmcnt(6)
	v_pk_mul_f32 v[36:37], v[38:39], s[2:3] op_sel_hi:[1,0]
	s_waitcnt vmcnt(4)
	v_pk_mul_f32 v[38:39], v[40:41], s[2:3] op_sel_hi:[1,0]
	s_waitcnt vmcnt(2)
	v_pk_mul_f32 v[40:41], v[42:43], s[2:3] op_sel_hi:[1,0]
	s_waitcnt vmcnt(0)
	v_pk_mul_f32 v[42:43], v[44:45], s[2:3] op_sel_hi:[1,0]
	ds_write_b32 v50, v30
	ds_write_b32 v52, v31
	ds_write_b32 v54, v32
	ds_write_b32 v56, v33
	ds_write_b32 v58, v34
	ds_write_b32 v60, v35
	ds_write_b32 v62, v36
	ds_write_b32 v64, v37
	ds_write_b32 v66, v38
	ds_write_b32 v68, v39
	ds_write_b32 v70, v40
	ds_write_b32 v72, v41
	ds_write_b32 v74, v42
	ds_write_b32 v76, v43
	s_cbranch_scc1 .LBB0_45
	s_waitcnt lgkmcnt(0)
	ds_read2_b32 v[22:23], v25 offset0:33 offset1:41
	ds_read2_b32 v[34:35], v25 offset1:8
	ds_read2_b32 v[36:37], v25 offset0:66 offset1:74
	ds_read2_b32 v[38:39], v25 offset0:99 offset1:107
	ds_read2_b32 v[40:41], v25 offset0:132 offset1:140
	ds_read2_b32 v[42:43], v25 offset0:165 offset1:173
	ds_read2_b32 v[44:45], v25 offset0:198 offset1:206
	ds_read2_b32 v[46:47], v25 offset0:231 offset1:239
	s_addk_i32 s30, 0x800
	s_ashr_i32 s15, s14, 31
	v_or_b32_e32 v4, s30, v24
	v_lshl_add_u64 v[48:49], s[14:15], 1, v[6:7]
	v_lshlrev_b64 v[50:51], 11, v[4:5]
	s_waitcnt lgkmcnt(6)
	v_cvt_pk_bf16_f32 v30, v34, v22
	s_waitcnt lgkmcnt(4)
	v_cvt_pk_bf16_f32 v31, v36, v38
	s_waitcnt lgkmcnt(2)
	v_cvt_pk_bf16_f32 v32, v40, v42
	s_waitcnt lgkmcnt(0)
	v_cvt_pk_bf16_f32 v33, v44, v46
	v_lshl_add_u64 v[50:51], v[48:49], 0, v[50:51]
	global_store_dwordx4 v[50:51], v[30:33], off
	v_or_b32_e32 v4, s30, v26
	s_nop 0
	v_cvt_pk_bf16_f32 v30, v35, v23
	v_cvt_pk_bf16_f32 v31, v37, v39
	v_cvt_pk_bf16_f32 v32, v41, v43
	v_cvt_pk_bf16_f32 v33, v45, v47
	ds_read2_b32 v[34:35], v25 offset0:49 offset1:57
	ds_read2_b32 v[36:37], v25 offset0:16 offset1:24
	ds_read2_b32 v[38:39], v25 offset0:82 offset1:90
	ds_read2_b32 v[40:41], v25 offset0:115 offset1:123
	ds_read2_b32 v[42:43], v25 offset0:148 offset1:156
	ds_read2_b32 v[44:45], v25 offset0:181 offset1:189
	ds_read2_b32 v[46:47], v25 offset0:214 offset1:222
	ds_read2_b32 v[50:51], v25 offset0:247 offset1:255
	v_lshlrev_b64 v[22:23], 11, v[4:5]
	v_lshl_add_u64 v[22:23], v[48:49], 0, v[22:23]
	v_or_b32_e32 v4, s30, v27
	global_store_dwordx4 v[22:23], v[30:33], off
	v_lshlrev_b64 v[22:23], 11, v[4:5]
	v_lshl_add_u64 v[22:23], v[48:49], 0, v[22:23]
	s_waitcnt lgkmcnt(6)
	v_cvt_pk_bf16_f32 v30, v36, v34
	s_waitcnt lgkmcnt(4)
	v_cvt_pk_bf16_f32 v31, v38, v40
	s_waitcnt lgkmcnt(2)
	v_cvt_pk_bf16_f32 v32, v42, v44
	s_waitcnt lgkmcnt(0)
	v_cvt_pk_bf16_f32 v33, v46, v50
	v_or_b32_e32 v4, s30, v28
	global_store_dwordx4 v[22:23], v[30:33], off
	v_lshlrev_b64 v[22:23], 11, v[4:5]
	v_lshl_add_u64 v[22:23], v[48:49], 0, v[22:23]
	v_cvt_pk_bf16_f32 v30, v37, v35
	v_cvt_pk_bf16_f32 v31, v39, v41
	v_cvt_pk_bf16_f32 v32, v43, v45
	v_cvt_pk_bf16_f32 v33, v47, v51
	global_store_dwordx4 v[22:23], v[30:33], off
	s_waitcnt lgkmcnt(0)

; #define LAS __attribute__((address_space(3)))
; __device__ __forceinline__ unsigned cvtpk(float lo, float hi) { return pg8::cvt_pk_bf16(lo, hi); }
; __device__ __forceinline__ void transpose_item(const float* W, int K, int N, int c0, int ncols, bf16_t* WT, int row_off, float scale, LAS float* scr, int item, int lane) {
;     const int nblk = ncols / 32, kb = item / nblk, nb = item % nblk, k0 = 64 * kb, n0 = 32 * nb;
; #pragma unroll 8
;     for (int i = 0; i < 32; ++i) { const int kk = 2 * i + (lane >> 5); scr[kk * 33 + (lane & 31)] = W[(size_t)(k0 + kk) * N + c0 + n0 + (lane & 31)] * scale; }
;     asm volatile("s_waitcnt lgkmcnt(0)" ::: "memory");
;     const int c = lane & 7;
; #pragma unroll
;     for (int j = 0; j < 4; ++j) { const int n = (lane >> 3) + 8 * j; const LAS float* s = scr + (8 * c) * 33 + n;
;         u32x4 o; o.x = cvtpk(s[0 * 33], s[1 * 33]); o.y = cvtpk(s[2 * 33], s[3 * 33]); o.z = cvtpk(s[4 * 33], s[5 * 33]); o.w = cvtpk(s[6 * 33], s[7 * 33]);
;         *(u32x4*)(WT + (size_t)(row_off + n0 + n) * K + k0 + 8 * c) = o; }
;     asm volatile("s_waitcnt lgkmcnt(0)" ::: "memory");
.LBB0_52:
	s_lshl_b32 s37, s15, 1
	s_lshl_b32 s40, s31, 1
	v_or_b32_e32 v29, s37, v3
	v_or_b32_e32 v30, s40, v4
	s_add_i32 s41, s37, 4
	s_add_i32 s42, s40, 4
	s_add_i32 s43, s37, 8
	s_add_i32 s44, s40, 8
	s_add_i32 s45, s37, 12
	s_add_i32 s46, s40, 12
	s_add_i32 s47, s37, 16
	s_add_i32 s48, s40, 16
	s_add_i32 s49, s37, 20
	s_add_i32 s50, s40, 20
	s_add_i32 s51, s37, 24
	s_add_i32 s52, s40, 24
	s_add_i32 s53, s37, 28
	s_add_i32 s54, s40, 28
	v_mad_i64_i32 v[30:31], s[38:39], v30, s34, v[22:23]
	v_mad_i64_i32 v[32:33], s[38:39], v29, s34, v[22:23]
	v_or_b32_e32 v29, s41, v3
	v_or_b32_e32 v34, s42, v4
	v_or_b32_e32 v40, s43, v3
	v_or_b32_e32 v38, s44, v4
	v_or_b32_e32 v44, s45, v3
	v_or_b32_e32 v42, s46, v4
	v_or_b32_e32 v48, s47, v3
	v_or_b32_e32 v46, s48, v4
	v_or_b32_e32 v52, s49, v3
	v_or_b32_e32 v50, s50, v4
	v_or_b32_e32 v56, s51, v3
	v_or_b32_e32 v54, s52, v4
	v_or_b32_e32 v60, s53, v3
	v_or_b32_e32 v58, s54, v4
	v_mad_i64_i32 v[34:35], s[38:39], v34, s34, v[22:23]
	v_mad_i64_i32 v[36:37], s[38:39], v29, s34, v[22:23]
	v_mad_i64_i32 v[38:39], s[38:39], v38, s34, v[22:23]
	v_mad_i64_i32 v[40:41], s[38:39], v40, s34, v[22:23]
	v_mad_i64_i32 v[42:43], s[38:39], v42, s34, v[22:23]
	v_mad_i64_i32 v[44:45], s[38:39], v44, s34, v[22:23]
	v_mad_i64_i32 v[46:47], s[38:39], v46, s34, v[22:23]
	v_mad_i64_i32 v[48:49], s[38:39], v48, s34, v[22:23]
	v_mad_i64_i32 v[50:51], s[38:39], v50, s34, v[22:23]
	v_mad_i64_i32 v[52:53], s[38:39], v52, s34, v[22:23]
	v_mad_i64_i32 v[54:55], s[38:39], v54, s34, v[22:23]
	v_mad_i64_i32 v[56:57], s[38:39], v56, s34, v[22:23]
	v_mad_i64_i32 v[58:59], s[38:39], v58, s34, v[22:23]
	v_mad_i64_i32 v[60:61], s[38:39], v60, s34, v[22:23]
	global_load_dword v29, v[30:31], off nt
	global_load_dword v62, v[32:33], off nt
	global_load_dword v63, v[34:35], off nt
	global_load_dword v64, v[36:37], off nt
	global_load_dword v65, v[38:39], off nt
	global_load_dword v66, v[40:41], off nt
	global_load_dword v67, v[42:43], off nt
	global_load_dword v68, v[44:45], off nt
	global_load_dword v69, v[46:47], off nt
	global_load_dword v70, v[48:49], off nt
	global_load_dword v71, v[50:51], off nt
	global_load_dword v72, v[52:53], off nt
	global_load_dword v73, v[54:55], off nt
	global_load_dword v74, v[56:57], off nt
	global_load_dword v75, v[58:59], off nt
	global_load_dword v76, v[60:61], off nt
	v_or_b32_e32 v32, s37, v1
	v_or_b32_e32 v30, s40, v0
	s_add_i32 s31, s31, 16
	s_add_i32 s15, s15, 16
	s_add_i32 s36, s36, -16
	v_mad_u64_u32 v[30:31], s[38:39], v30, s33, v[2:3]
	v_mad_u64_u32 v[32:33], s[38:39], v32, s33, v[2:3]
	v_or_b32_e32 v31, s41, v1
	v_or_b32_e32 v33, s42, v0
	v_or_b32_e32 v40, s43, v1
	v_or_b32_e32 v38, s44, v0
	v_or_b32_e32 v44, s45, v1
	v_or_b32_e32 v42, s46, v0
	v_or_b32_e32 v48, s47, v1
	v_or_b32_e32 v46, s48, v0
	v_or_b32_e32 v52, s49, v1
	v_or_b32_e32 v50, s50, v0
	v_or_b32_e32 v56, s51, v1
	v_or_b32_e32 v54, s52, v0
	v_or_b32_e32 v60, s53, v1
	v_or_b32_e32 v58, s54, v0
	s_cmp_lg_u32 s36, 0
	v_mad_u64_u32 v[34:35], s[38:39], v33, s33, v[2:3]
	v_mad_u64_u32 v[36:37], s[38:39], v31, s33, v[2:3]
	v_mad_u64_u32 v[38:39], s[38:39], v38, s33, v[2:3]
	v_mad_u64_u32 v[40:41], s[38:39], v40, s33, v[2:3]
	v_mad_u64_u32 v[42:43], s[38:39], v42, s33, v[2:3]
	v_mad_u64_u32 v[44:45], s[38:39], v44, s33, v[2:3]
	v_mad_u64_u32 v[46:47], s[38:39], v46, s33, v[2:3]
	v_mad_u64_u32 v[48:49], s[38:39], v48, s33, v[2:3]
	v_mad_u64_u32 v[50:51], s[38:39], v50, s33, v[2:3]
	v_mad_u64_u32 v[52:53], s[38:39], v52, s33, v[2:3]
	v_mad_u64_u32 v[54:55], s[38:39], v54, s33, v[2:3]
	v_mad_u64_u32 v[56:57], s[38:39], v56, s33, v[2:3]
	v_mad_u64_u32 v[58:59], s[38:39], v58, s33, v[2:3]
	v_mad_u64_u32 v[60:61], s[38:39], v60, s33, v[2:3]
	s_waitcnt vmcnt(15)
	ds_write_b32 v30, v29
	s_waitcnt vmcnt(14)
	ds_write_b32 v32, v62
	s_waitcnt vmcnt(13)
	ds_write_b32 v34, v63
	s_waitcnt vmcnt(12)
	ds_write_b32 v36, v64
	s_waitcnt vmcnt(11)
	ds_write_b32 v38, v65
	s_waitcnt vmcnt(10)
	ds_write_b32 v40, v66
	s_waitcnt vmcnt(9)
	ds_write_b32 v42, v67
	s_waitcnt vmcnt(8)
	ds_write_b32 v44, v68
	s_waitcnt vmcnt(7)
	ds_write_b32 v46, v69
	s_waitcnt vmcnt(6)
	ds_write_b32 v48, v70
	s_waitcnt vmcnt(5)
	ds_write_b32 v50, v71
	s_waitcnt vmcnt(4)
	ds_write_b32 v52, v72
	s_waitcnt vmcnt(3)
	ds_write_b32 v54, v73
	s_waitcnt vmcnt(2)
	ds_write_b32 v56, v74
	s_waitcnt vmcnt(1)
	ds_write_b32 v58, v75
	s_waitcnt vmcnt(0)
	ds_write_b32 v60, v76
	s_cbranch_scc1 .LBB0_52
	s_waitcnt lgkmcnt(0)
	ds_read2_b32 v[22:23], v25 offset0:33 offset1:41
	ds_read2_b32 v[34:35], v25 offset1:8
	ds_read2_b32 v[36:37], v25 offset0:66 offset1:74
	ds_read2_b32 v[38:39], v25 offset0:99 offset1:107
	ds_read2_b32 v[40:41], v25 offset0:132 offset1:140
	ds_read2_b32 v[42:43], v25 offset0:165 offset1:173
	ds_read2_b32 v[44:45], v25 offset0:198 offset1:206
	ds_read2_b32 v[46:47], v25 offset0:231 offset1:239
	s_addk_i32 s30, 0xe00
	s_ashr_i32 s15, s14, 31
	v_or_b32_e32 v4, s30, v24
	v_lshl_add_u64 v[48:49], s[14:15], 1, v[6:7]
	v_lshlrev_b64 v[50:51], 11, v[4:5]
	s_waitcnt lgkmcnt(6)
	v_cvt_pk_bf16_f32 v30, v34, v22
	s_waitcnt lgkmcnt(4)
	v_cvt_pk_bf16_f32 v31, v36, v38
	s_waitcnt lgkmcnt(2)
	v_cvt_pk_bf16_f32 v32, v40, v42
	s_waitcnt lgkmcnt(0)
	v_cvt_pk_bf16_f32 v33, v44, v46
	v_lshl_add_u64 v[50:51], v[48:49], 0, v[50:51]
	global_store_dwordx4 v[50:51], v[30:33], off
	v_or_b32_e32 v4, s30, v26
	s_nop 0
	v_cvt_pk_bf16_f32 v30, v35, v23
	v_cvt_pk_bf16_f32 v31, v37, v39
	v_cvt_pk_bf16_f32 v32, v41, v43
	v_cvt_pk_bf16_f32 v33, v45, v47
	ds_read2_b32 v[34:35], v25 offset0:49 offset1:57
	ds_read2_b32 v[36:37], v25 offset0:16 offset1:24
	ds_read2_b32 v[38:39], v25 offset0:82 offset1:90
	ds_read2_b32 v[40:41], v25 offset0:115 offset1:123
	ds_read2_b32 v[42:43], v25 offset0:148 offset1:156
	ds_read2_b32 v[44:45], v25 offset0:181 offset1:189
	ds_read2_b32 v[46:47], v25 offset0:214 offset1:222
	ds_read2_b32 v[50:51], v25 offset0:247 offset1:255
	v_lshlrev_b64 v[22:23], 11, v[4:5]
	v_lshl_add_u64 v[22:23], v[48:49], 0, v[22:23]
	v_or_b32_e32 v4, s30, v27
	global_store_dwordx4 v[22:23], v[30:33], off
	v_lshlrev_b64 v[22:23], 11, v[4:5]
	v_lshl_add_u64 v[22:23], v[48:49], 0, v[22:23]
	s_waitcnt lgkmcnt(6)
	v_cvt_pk_bf16_f32 v30, v36, v34
	s_waitcnt lgkmcnt(4)
	v_cvt_pk_bf16_f32 v31, v38, v40
	s_waitcnt lgkmcnt(2)
	v_cvt_pk_bf16_f32 v32, v42, v44
	s_waitcnt lgkmcnt(0)
	v_cvt_pk_bf16_f32 v33, v46, v50
	v_or_b32_e32 v4, s30, v28
	global_store_dwordx4 v[22:23], v[30:33], off
	v_lshlrev_b64 v[22:23], 11, v[4:5]
	v_lshl_add_u64 v[22:23], v[48:49], 0, v[22:23]
	v_cvt_pk_bf16_f32 v30, v37, v35
	v_cvt_pk_bf16_f32 v31, v39, v41
	v_cvt_pk_bf16_f32 v32, v43, v45
	v_cvt_pk_bf16_f32 v33, v47, v51
	global_store_dwordx4 v[22:23], v[30:33], off
	s_waitcnt lgkmcnt(0)

; #define LAS __attribute__((address_space(3)))
; __device__ __forceinline__ unsigned cvtpk(float lo, float hi) { return pg8::cvt_pk_bf16(lo, hi); }
; __device__ __forceinline__ void transpose_item(const float* W, int K, int N, int c0, int ncols, bf16_t* WT, int row_off, float scale, LAS float* scr, int item, int lane) {
;     ...
; #pragma unroll 8
;     for (int i = 0; i < 32; ++i) { const int kk = 2 * i + (lane >> 5); scr[kk * 33 + (lane & 31)] = W[(size_t)(k0 + kk) * N + c0 + n0 + (lane & 31)] * scale; }
;     asm volatile("s_waitcnt lgkmcnt(0)" ::: "memory");
;     const int c = lane & 7;
; #pragma unroll
;     for (int j = 0; j < 4; ++j) { const int n = (lane >> 3) + 8 * j; const LAS float* s = scr + (8 * c) * 33 + n;
;         u32x4 o; o.x = cvtpk(s[0 * 33], s[1 * 33]); o.y = cvtpk(s[2 * 33], s[3 * 33]); o.z = cvtpk(s[4 * 33], s[5 * 33]); o.w = cvtpk(s[6 * 33], s[7 * 33]);
;         *(u32x4*)(WT + (size_t)(row_off + n0 + n) * K + k0 + 8 * c) = o; }
.LBB0_59:
	s_lshl_b32 s37, s15, 1
	s_lshl_b32 s40, s31, 1
	v_or_b32_e32 v29, s37, v3
	v_or_b32_e32 v30, s40, v4
	s_add_i32 s41, s37, 4
	s_add_i32 s42, s40, 4
	s_add_i32 s43, s37, 8
	s_add_i32 s44, s40, 8
	s_add_i32 s45, s37, 12
	s_add_i32 s46, s40, 12
	s_add_i32 s47, s37, 16
	s_add_i32 s48, s40, 16
	s_add_i32 s49, s37, 20
	s_add_i32 s50, s40, 20
	s_add_i32 s51, s37, 24
	s_add_i32 s52, s40, 24
	s_add_i32 s53, s37, 28
	s_add_i32 s54, s40, 28
	v_mad_i64_i32 v[30:31], s[38:39], v30, s34, v[22:23]
	v_mad_i64_i32 v[32:33], s[38:39], v29, s34, v[22:23]
	v_or_b32_e32 v29, s41, v3
	v_or_b32_e32 v34, s42, v4
	v_or_b32_e32 v40, s43, v3
	v_or_b32_e32 v38, s44, v4
	v_or_b32_e32 v44, s45, v3
	v_or_b32_e32 v42, s46, v4
	v_or_b32_e32 v48, s47, v3
	v_or_b32_e32 v46, s48, v4
	v_or_b32_e32 v52, s49, v3
	v_or_b32_e32 v50, s50, v4
	v_or_b32_e32 v56, s51, v3
	v_or_b32_e32 v54, s52, v4
	v_or_b32_e32 v60, s53, v3
	v_or_b32_e32 v58, s54, v4
	v_mad_i64_i32 v[34:35], s[38:39], v34, s34, v[22:23]
	v_mad_i64_i32 v[36:37], s[38:39], v29, s34, v[22:23]
	v_mad_i64_i32 v[38:39], s[38:39], v38, s34, v[22:23]
	v_mad_i64_i32 v[40:41], s[38:39], v40, s34, v[22:23]
	v_mad_i64_i32 v[42:43], s[38:39], v42, s34, v[22:23]
	v_mad_i64_i32 v[44:45], s[38:39], v44, s34, v[22:23]
	v_mad_i64_i32 v[46:47], s[38:39], v46, s34, v[22:23]
	v_mad_i64_i32 v[48:49], s[38:39], v48, s34, v[22:23]
	v_mad_i64_i32 v[50:51], s[38:39], v50, s34, v[22:23]
	v_mad_i64_i32 v[52:53], s[38:39], v52, s34, v[22:23]
	v_mad_i64_i32 v[54:55], s[38:39], v54, s34, v[22:23]
	v_mad_i64_i32 v[56:57], s[38:39], v56, s34, v[22:23]
	v_mad_i64_i32 v[58:59], s[38:39], v58, s34, v[22:23]
	v_mad_i64_i32 v[60:61], s[38:39], v60, s34, v[22:23]
	global_load_dword v29, v[30:31], off nt
	global_load_dword v62, v[32:33], off nt
	global_load_dword v63, v[34:35], off nt
	global_load_dword v64, v[36:37], off nt
	global_load_dword v65, v[38:39], off nt
	global_load_dword v66, v[40:41], off nt
	global_load_dword v67, v[42:43], off nt
	global_load_dword v68, v[44:45], off nt
	global_load_dword v69, v[46:47], off nt
	global_load_dword v70, v[48:49], off nt
	global_load_dword v71, v[50:51], off nt
	global_load_dword v72, v[52:53], off nt
	global_load_dword v73, v[54:55], off nt
	global_load_dword v74, v[56:57], off nt
	global_load_dword v75, v[58:59], off nt
	global_load_dword v76, v[60:61], off nt
	v_or_b32_e32 v32, s37, v1
	v_or_b32_e32 v30, s40, v0
	s_add_i32 s31, s31, 16
	s_add_i32 s15, s15, 16
	s_add_i32 s36, s36, -16
	v_mad_u64_u32 v[30:31], s[38:39], v30, s33, v[2:3]
	v_mad_u64_u32 v[32:33], s[38:39], v32, s33, v[2:3]
	v_or_b32_e32 v31, s41, v1
	v_or_b32_e32 v33, s42, v0
	v_or_b32_e32 v40, s43, v1
	v_or_b32_e32 v38, s44, v0
	v_or_b32_e32 v44, s45, v1
	v_or_b32_e32 v42, s46, v0
	v_or_b32_e32 v48, s47, v1
	v_or_b32_e32 v46, s48, v0
	v_or_b32_e32 v52, s49, v1
	v_or_b32_e32 v50, s50, v0
	v_or_b32_e32 v56, s51, v1
	v_or_b32_e32 v54, s52, v0
	v_or_b32_e32 v60, s53, v1
	v_or_b32_e32 v58, s54, v0
	s_cmp_lg_u32 s36, 0
	v_mad_u64_u32 v[34:35], s[38:39], v33, s33, v[2:3]
	v_mad_u64_u32 v[36:37], s[38:39], v31, s33, v[2:3]
	v_mad_u64_u32 v[38:39], s[38:39], v38, s33, v[2:3]
	v_mad_u64_u32 v[40:41], s[38:39], v40, s33, v[2:3]
	v_mad_u64_u32 v[42:43], s[38:39], v42, s33, v[2:3]
	v_mad_u64_u32 v[44:45], s[38:39], v44, s33, v[2:3]
	v_mad_u64_u32 v[46:47], s[38:39], v46, s33, v[2:3]
	v_mad_u64_u32 v[48:49], s[38:39], v48, s33, v[2:3]
	v_mad_u64_u32 v[50:51], s[38:39], v50, s33, v[2:3]
	v_mad_u64_u32 v[52:53], s[38:39], v52, s33, v[2:3]
	v_mad_u64_u32 v[54:55], s[38:39], v54, s33, v[2:3]
	v_mad_u64_u32 v[56:57], s[38:39], v56, s33, v[2:3]
	v_mad_u64_u32 v[58:59], s[38:39], v58, s33, v[2:3]
	v_mad_u64_u32 v[60:61], s[38:39], v60, s33, v[2:3]
	s_waitcnt vmcnt(15)
	ds_write_b32 v30, v29
	s_waitcnt vmcnt(14)
	ds_write_b32 v32, v62
	s_waitcnt vmcnt(13)
	ds_write_b32 v34, v63
	s_waitcnt vmcnt(12)
	ds_write_b32 v36, v64
	s_waitcnt vmcnt(11)
	ds_write_b32 v38, v65
	s_waitcnt vmcnt(10)
	ds_write_b32 v40, v66
	s_waitcnt vmcnt(9)
	ds_write_b32 v42, v67
	s_waitcnt vmcnt(8)
	ds_write_b32 v44, v68
	s_waitcnt vmcnt(7)
	ds_write_b32 v46, v69
	s_waitcnt vmcnt(6)
	ds_write_b32 v48, v70
	s_waitcnt vmcnt(5)
	ds_write_b32 v50, v71
	s_waitcnt vmcnt(4)
	ds_write_b32 v52, v72
	s_waitcnt vmcnt(3)
	ds_write_b32 v54, v73
	s_waitcnt vmcnt(2)
	ds_write_b32 v56, v74
	s_waitcnt vmcnt(1)
	ds_write_b32 v58, v75
	s_waitcnt vmcnt(0)
	ds_write_b32 v60, v76
	s_cbranch_scc1 .LBB0_59
	s_waitcnt lgkmcnt(0)
	ds_read2_b32 v[22:23], v25 offset0:33 offset1:41
	ds_read2_b32 v[34:35], v25 offset1:8
	ds_read2_b32 v[36:37], v25 offset0:66 offset1:74
	ds_read2_b32 v[38:39], v25 offset0:99 offset1:107
	ds_read2_b32 v[40:41], v25 offset0:132 offset1:140
	ds_read2_b32 v[42:43], v25 offset0:165 offset1:173
	ds_read2_b32 v[44:45], v25 offset0:198 offset1:206
	ds_read2_b32 v[46:47], v25 offset0:231 offset1:239
	s_bfe_u32 s37, s30, 0x10005
	s_and_b32 s30, s30, 0xffffffc0
	s_or_b32 s30, s30, s37
	s_addk_i32 s30, 0x1400
	s_ashr_i32 s15, s14, 31
	v_lshl_or_b32 v4, v24, 1, s30
	v_lshl_add_u64 v[48:49], s[14:15], 1, v[6:7]
	v_lshlrev_b64 v[50:51], 11, v[4:5]
	s_waitcnt lgkmcnt(6)
	v_cvt_pk_bf16_f32 v30, v34, v22
	s_waitcnt lgkmcnt(4)
	v_cvt_pk_bf16_f32 v31, v36, v38
	s_waitcnt lgkmcnt(2)
	v_cvt_pk_bf16_f32 v32, v40, v42
	s_waitcnt lgkmcnt(0)
	v_cvt_pk_bf16_f32 v33, v44, v46
	v_lshl_add_u64 v[50:51], v[48:49], 0, v[50:51]
	global_store_dwordx4 v[50:51], v[30:33], off
	v_lshl_or_b32 v4, v26, 1, s30
	s_nop 0
	v_cvt_pk_bf16_f32 v30, v35, v23
	v_cvt_pk_bf16_f32 v31, v37, v39
	v_cvt_pk_bf16_f32 v32, v41, v43
	v_cvt_pk_bf16_f32 v33, v45, v47
	ds_read2_b32 v[34:35], v25 offset0:49 offset1:57
	ds_read2_b32 v[36:37], v25 offset0:16 offset1:24
	ds_read2_b32 v[38:39], v25 offset0:82 offset1:90
	ds_read2_b32 v[40:41], v25 offset0:115 offset1:123
	ds_read2_b32 v[42:43], v25 offset0:148 offset1:156
	ds_read2_b32 v[44:45], v25 offset0:181 offset1:189
	ds_read2_b32 v[46:47], v25 offset0:214 offset1:222
	ds_read2_b32 v[50:51], v25 offset0:247 offset1:255
	v_lshlrev_b64 v[22:23], 11, v[4:5]
	v_lshl_add_u64 v[22:23], v[48:49], 0, v[22:23]
	v_lshl_or_b32 v4, v27, 1, s30
	global_store_dwordx4 v[22:23], v[30:33], off
	v_lshlrev_b64 v[22:23], 11, v[4:5]
	v_lshl_add_u64 v[22:23], v[48:49], 0, v[22:23]
	s_waitcnt lgkmcnt(6)
	v_cvt_pk_bf16_f32 v30, v36, v34
	s_waitcnt lgkmcnt(4)
	v_cvt_pk_bf16_f32 v31, v38, v40
	s_waitcnt lgkmcnt(2)
	v_cvt_pk_bf16_f32 v32, v42, v44
	s_waitcnt lgkmcnt(0)
	v_cvt_pk_bf16_f32 v33, v46, v50
	v_lshl_or_b32 v4, v28, 1, s30
	global_store_dwordx4 v[22:23], v[30:33], off
	v_lshlrev_b64 v[22:23], 11, v[4:5]
	v_lshl_add_u64 v[22:23], v[48:49], 0, v[22:23]
	v_cvt_pk_bf16_f32 v30, v37, v35
	v_cvt_pk_bf16_f32 v31, v39, v41
	v_cvt_pk_bf16_f32 v32, v43, v45
	v_cvt_pk_bf16_f32 v33, v47, v51
	global_store_dwordx4 v[22:23], v[30:33], off
	s_waitcnt lgkmcnt(0)

; #define LAS __attribute__((address_space(3)))
; __device__ __forceinline__ unsigned cvtpk(float lo, float hi) { return pg8::cvt_pk_bf16(lo, hi); }
; __device__ __forceinline__ void transpose_item(const float* W, int K, int N, int c0, int ncols, bf16_t* WT, int row_off, float scale, LAS float* scr, int item, int lane) {
;     ...
; #pragma unroll 8
;     for (int i = 0; i < 32; ++i) { const int kk = 2 * i + (lane >> 5); scr[kk * 33 + (lane & 31)] = W[(size_t)(k0 + kk) * N + c0 + n0 + (lane & 31)] * scale; }
;     asm volatile("s_waitcnt lgkmcnt(0)" ::: "memory");
;     const int c = lane & 7;
; #pragma unroll
;     for (int j = 0; j < 4; ++j) { const int n = (lane >> 3) + 8 * j; const LAS float* s = scr + (8 * c) * 33 + n;
;         u32x4 o; o.x = cvtpk(s[0 * 33], s[1 * 33]); o.y = cvtpk(s[2 * 33], s[3 * 33]); o.z = cvtpk(s[4 * 33], s[5 * 33]); o.w = cvtpk(s[6 * 33], s[7 * 33]);
;         *(u32x4*)(WT + (size_t)(row_off + n0 + n) * K + k0 + 8 * c) = o; }
.LBB0_65:
	s_lshl_b32 s31, s5, 1
	s_lshl_b32 s35, s15, 1
	v_or_b32_e32 v29, s31, v3
	v_or_b32_e32 v30, s35, v4
	s_add_i32 s38, s31, 4
	s_add_i32 s39, s35, 4
	s_add_i32 s40, s31, 8
	s_add_i32 s41, s35, 8
	s_add_i32 s42, s31, 12
	s_add_i32 s43, s35, 12
	s_add_i32 s44, s31, 16
	s_add_i32 s45, s35, 16
	s_add_i32 s46, s31, 20
	s_add_i32 s47, s35, 20
	s_add_i32 s48, s31, 24
	s_add_i32 s49, s35, 24
	s_add_i32 s50, s31, 28
	s_add_i32 s51, s35, 28
	v_mad_i64_i32 v[30:31], s[36:37], v30, s34, v[22:23]
	v_mad_i64_i32 v[32:33], s[36:37], v29, s34, v[22:23]
	v_or_b32_e32 v29, s38, v3
	v_or_b32_e32 v34, s39, v4
	v_or_b32_e32 v40, s40, v3
	v_or_b32_e32 v38, s41, v4
	v_or_b32_e32 v44, s42, v3
	v_or_b32_e32 v42, s43, v4
	v_or_b32_e32 v48, s44, v3
	v_or_b32_e32 v46, s45, v4
	v_or_b32_e32 v52, s46, v3
	v_or_b32_e32 v50, s47, v4
	v_or_b32_e32 v56, s48, v3
	v_or_b32_e32 v54, s49, v4
	v_or_b32_e32 v60, s50, v3
	v_or_b32_e32 v58, s51, v4
	v_mad_i64_i32 v[34:35], s[36:37], v34, s34, v[22:23]
	v_mad_i64_i32 v[36:37], s[36:37], v29, s34, v[22:23]
	v_mad_i64_i32 v[38:39], s[36:37], v38, s34, v[22:23]
	v_mad_i64_i32 v[40:41], s[36:37], v40, s34, v[22:23]
	v_mad_i64_i32 v[42:43], s[36:37], v42, s34, v[22:23]
	v_mad_i64_i32 v[44:45], s[36:37], v44, s34, v[22:23]
	v_mad_i64_i32 v[46:47], s[36:37], v46, s34, v[22:23]
	v_mad_i64_i32 v[48:49], s[36:37], v48, s34, v[22:23]
	v_mad_i64_i32 v[50:51], s[36:37], v50, s34, v[22:23]
	v_mad_i64_i32 v[52:53], s[36:37], v52, s34, v[22:23]
	v_mad_i64_i32 v[54:55], s[36:37], v54, s34, v[22:23]
	v_mad_i64_i32 v[56:57], s[36:37], v56, s34, v[22:23]
	v_mad_i64_i32 v[58:59], s[36:37], v58, s34, v[22:23]
	v_mad_i64_i32 v[60:61], s[36:37], v60, s34, v[22:23]
	global_load_dword v29, v[30:31], off nt
	global_load_dword v62, v[32:33], off nt
	global_load_dword v63, v[34:35], off nt
	global_load_dword v64, v[36:37], off nt
	global_load_dword v65, v[38:39], off nt
	global_load_dword v66, v[40:41], off nt
	global_load_dword v67, v[42:43], off nt
	global_load_dword v68, v[44:45], off nt
	global_load_dword v69, v[46:47], off nt
	global_load_dword v70, v[48:49], off nt
	global_load_dword v71, v[50:51], off nt
	global_load_dword v72, v[52:53], off nt
	global_load_dword v73, v[54:55], off nt
	global_load_dword v74, v[56:57], off nt
	global_load_dword v75, v[58:59], off nt
	global_load_dword v76, v[60:61], off nt
	v_or_b32_e32 v32, s31, v1
	v_or_b32_e32 v30, s35, v0
	s_add_i32 s15, s15, 16
	s_add_i32 s5, s5, 16
	s_add_i32 s30, s30, -16
	v_mad_u64_u32 v[30:31], s[36:37], v30, s33, v[2:3]
	v_mad_u64_u32 v[32:33], s[36:37], v32, s33, v[2:3]
	v_or_b32_e32 v31, s38, v1
	v_or_b32_e32 v33, s39, v0
	v_or_b32_e32 v40, s40, v1
	v_or_b32_e32 v38, s41, v0
	v_or_b32_e32 v44, s42, v1
	v_or_b32_e32 v42, s43, v0
	v_or_b32_e32 v48, s44, v1
	v_or_b32_e32 v46, s45, v0
	v_or_b32_e32 v52, s46, v1
	v_or_b32_e32 v50, s47, v0
	v_or_b32_e32 v56, s48, v1
	v_or_b32_e32 v54, s49, v0
	v_or_b32_e32 v60, s50, v1
	v_or_b32_e32 v58, s51, v0
	s_cmp_lg_u32 s30, 0
	v_mad_u64_u32 v[34:35], s[36:37], v33, s33, v[2:3]
	v_mad_u64_u32 v[36:37], s[36:37], v31, s33, v[2:3]
	v_mad_u64_u32 v[38:39], s[36:37], v38, s33, v[2:3]
	v_mad_u64_u32 v[40:41], s[36:37], v40, s33, v[2:3]
	v_mad_u64_u32 v[42:43], s[36:37], v42, s33, v[2:3]
	v_mad_u64_u32 v[44:45], s[36:37], v44, s33, v[2:3]
	v_mad_u64_u32 v[46:47], s[36:37], v46, s33, v[2:3]
	v_mad_u64_u32 v[48:49], s[36:37], v48, s33, v[2:3]
	v_mad_u64_u32 v[50:51], s[36:37], v50, s33, v[2:3]
	v_mad_u64_u32 v[52:53], s[36:37], v52, s33, v[2:3]
	v_mad_u64_u32 v[54:55], s[36:37], v54, s33, v[2:3]
	v_mad_u64_u32 v[56:57], s[36:37], v56, s33, v[2:3]
	v_mad_u64_u32 v[58:59], s[36:37], v58, s33, v[2:3]
	v_mad_u64_u32 v[60:61], s[36:37], v60, s33, v[2:3]
	s_waitcnt vmcnt(15)
	ds_write_b32 v30, v29
	s_waitcnt vmcnt(14)
	ds_write_b32 v32, v62
	s_waitcnt vmcnt(13)
	ds_write_b32 v34, v63
	s_waitcnt vmcnt(12)
	ds_write_b32 v36, v64
	s_waitcnt vmcnt(11)
	ds_write_b32 v38, v65
	s_waitcnt vmcnt(10)
	ds_write_b32 v40, v66
	s_waitcnt vmcnt(9)
	ds_write_b32 v42, v67
	s_waitcnt vmcnt(8)
	ds_write_b32 v44, v68
	s_waitcnt vmcnt(7)
	ds_write_b32 v46, v69
	s_waitcnt vmcnt(6)
	ds_write_b32 v48, v70
	s_waitcnt vmcnt(5)
	ds_write_b32 v50, v71
	s_waitcnt vmcnt(4)
	ds_write_b32 v52, v72
	s_waitcnt vmcnt(3)
	ds_write_b32 v54, v73
	s_waitcnt vmcnt(2)
	ds_write_b32 v56, v74
	s_waitcnt vmcnt(1)
	ds_write_b32 v58, v75
	s_waitcnt vmcnt(0)
	ds_write_b32 v60, v76
	s_cbranch_scc1 .LBB0_65
	s_waitcnt lgkmcnt(0)
	ds_read2_b32 v[22:23], v25 offset0:33 offset1:41
	ds_read2_b32 v[34:35], v25 offset1:8
	ds_read2_b32 v[36:37], v25 offset0:66 offset1:74
	ds_read2_b32 v[38:39], v25 offset0:99 offset1:107
	ds_read2_b32 v[40:41], v25 offset0:132 offset1:140
	ds_read2_b32 v[42:43], v25 offset0:165 offset1:173
	ds_read2_b32 v[44:45], v25 offset0:198 offset1:206
	ds_read2_b32 v[46:47], v25 offset0:231 offset1:239
	s_addk_i32 s14, 0x1e00
	s_ashr_i32 s5, s4, 31
	v_or_b32_e32 v4, s14, v24
	v_lshl_add_u64 v[48:49], s[4:5], 1, v[6:7]
	v_lshlrev_b64 v[50:51], 11, v[4:5]
	s_waitcnt lgkmcnt(6)
	v_cvt_pk_bf16_f32 v30, v34, v22
	s_waitcnt lgkmcnt(4)
	v_cvt_pk_bf16_f32 v31, v36, v38
	s_waitcnt lgkmcnt(2)
	v_cvt_pk_bf16_f32 v32, v40, v42
	s_waitcnt lgkmcnt(0)
	v_cvt_pk_bf16_f32 v33, v44, v46
	v_lshl_add_u64 v[50:51], v[48:49], 0, v[50:51]
	global_store_dwordx4 v[50:51], v[30:33], off
	v_or_b32_e32 v4, s14, v26
	s_nop 0
	v_cvt_pk_bf16_f32 v30, v35, v23
	v_cvt_pk_bf16_f32 v31, v37, v39
	v_cvt_pk_bf16_f32 v32, v41, v43
	v_cvt_pk_bf16_f32 v33, v45, v47
	ds_read2_b32 v[34:35], v25 offset0:49 offset1:57
	ds_read2_b32 v[36:37], v25 offset0:16 offset1:24
	ds_read2_b32 v[38:39], v25 offset0:82 offset1:90
	ds_read2_b32 v[40:41], v25 offset0:115 offset1:123
	ds_read2_b32 v[42:43], v25 offset0:148 offset1:156
	ds_read2_b32 v[44:45], v25 offset0:181 offset1:189
	ds_read2_b32 v[46:47], v25 offset0:214 offset1:222
	ds_read2_b32 v[50:51], v25 offset0:247 offset1:255
	v_lshlrev_b64 v[22:23], 11, v[4:5]
	v_lshl_add_u64 v[22:23], v[48:49], 0, v[22:23]
	v_or_b32_e32 v4, s14, v27
	global_store_dwordx4 v[22:23], v[30:33], off
	v_lshlrev_b64 v[22:23], 11, v[4:5]
	v_lshl_add_u64 v[22:23], v[48:49], 0, v[22:23]
	s_waitcnt lgkmcnt(6)
	v_cvt_pk_bf16_f32 v30, v36, v34
	s_waitcnt lgkmcnt(4)
	v_cvt_pk_bf16_f32 v31, v38, v40
	s_waitcnt lgkmcnt(2)
	v_cvt_pk_bf16_f32 v32, v42, v44
	s_waitcnt lgkmcnt(0)
	v_cvt_pk_bf16_f32 v33, v46, v50
	v_or_b32_e32 v4, s14, v28
	global_store_dwordx4 v[22:23], v[30:33], off
	v_lshlrev_b64 v[22:23], 11, v[4:5]
	v_lshl_add_u64 v[22:23], v[48:49], 0, v[22:23]
	v_cvt_pk_bf16_f32 v30, v37, v35
	v_cvt_pk_bf16_f32 v31, v39, v41
	v_cvt_pk_bf16_f32 v32, v43, v45
	v_cvt_pk_bf16_f32 v33, v47, v51
	global_store_dwordx4 v[22:23], v[30:33], off
	s_waitcnt lgkmcnt(0)
	s_branch .LBB0_21
